# v46 + attention phase: one static s_setprio 1 for waves 4..7 at phase entry, reset to 0 at phase exit
# speedup vs baseline: 1.0129x; 1.0129x over previous
.LBB0_1588:
	s_or_b64 exec, exec, s[0:1]
	v_cmp_gt_u32_e32 vcc, 0x100, v229
	s_cbranch_vccnz .Latt_prio_done
	s_setprio 1
.Latt_prio_done:
	s_mov_b64 s[0:1], s[74:75]
	s_waitcnt lgkmcnt(0)
	v_mov_b32_e32 v0, v229
	s_mov_b32 s33, s2
	s_and_b64 vcc, exec, s[84:85]
	s_barrier
	s_cbranch_vccnz .LBB0_1590
	s_cmpk_gt_i32 s33, 0x1ff
	s_cbranch_scc0 .LBB0_1591
	s_branch .LBB0_1678

.LBB0_1678:
	s_setprio 0
	s_mov_b64 s[4:5], s[74:75]
	s_getreg_b32 s8, hwreg(HW_REG_XCC_ID, 0, 4)
	s_waitcnt vmcnt(0)
	s_barrier
	s_and_saveexec_b64 s[0:1], s[78:79]
	s_cbranch_execz .LBB0_1730
	s_add_i32 s9, 0, 0x23fc0
	v_mov_b32_e32 v0, s9
	s_load_dwordx2 s[4:5], s[4:5], 0x90
	s_waitcnt vmcnt(0) expcnt(0) lgkmcnt(0)
	ds_read_b32 v2, v0
	s_add_i32 s9, 0, 0x23fc4
	v_mov_b32_e32 v0, s9
	ds_read_b32 v0, v0
	s_and_b32 s33, s8, 15
	s_waitcnt lgkmcnt(1)
	v_cmp_ne_u32_e32 vcc, 0, v2
	s_cbranch_vccnz .LBB0_1694
	s_load_dwordx2 s[12:13], s[76:77], 0x4
	s_add_u32 s8, s4, 0x5700200
	s_addc_u32 s9, s5, 0
	s_add_u32 s10, s4, 0x5700400
	s_addc_u32 s11, s5, 0
	s_waitcnt lgkmcnt(0)
	s_mul_i32 s50, s12, s90
	s_add_u32 s12, s4, 0x5700500
	s_mul_i32 s50, s50, s13
	s_addc_u32 s13, s5, 0
	s_add_u32 s14, s4, 0x5700600
	s_addc_u32 s15, s5, 0
	s_add_u32 s16, s4, 0x5700700
	s_addc_u32 s17, s5, 0
	s_add_u32 s18, s4, 0x5700800
	s_addc_u32 s19, s5, 0
	s_add_u32 s20, s4, 0x5700900
	s_addc_u32 s21, s5, 0
	s_add_u32 s22, s4, 0x5700a00
	s_addc_u32 s23, s5, 0
	s_add_u32 s24, s4, 0x5700b00
	s_addc_u32 s25, s5, 0
	s_add_u32 s26, s4, 0x5700c00
	s_addc_u32 s27, s5, 0
	s_add_u32 s28, s4, 0x5700d00
	s_addc_u32 s29, s5, 0
	s_add_u32 s30, s4, 0x5700e00
	s_addc_u32 s31, s5, 0
	s_add_u32 s34, s4, 0x5700f00
	s_addc_u32 s35, s5, 0
	s_add_u32 s36, s4, 0x5701000
	s_addc_u32 s37, s5, 0
	s_add_u32 s38, s4, 0x5701100
	s_addc_u32 s39, s5, 0
	s_add_u32 s40, s4, 0x5701200
	s_addc_u32 s41, s5, 0
	s_add_u32 s42, s4, 0x5701300
	s_addc_u32 s43, s5, 0
	s_mov_b32 s51, 1
	v_mov_b32_e32 v16, 0
	s_branch .LBB0_1682
